# fused hyena middle step with 1-bit LDS piece swizzle; spectrum loads issued at the start of the forward head
# speedup vs baseline: 1.1771x; 1.0024x over previous
; __device__ __forceinline__ void fft_mid(float2* Z, const f16x2* Hp, int tid){
;   _Pragma("unroll 4") for (int i=0;i<8;++i){ int base=(tid<<2)+i*2048;
;     u32x4 hw=*(const u32x4*)(Hp+base);
; __device__ __forceinline__ void phase_hyena(KP kp_, int hf){ asm volatile("" : "+s"(kp_)); const Params p=load_params(kp_);
;     ...
;         const f16x2* Hp = st==1 ? H0p : H1p;
;         fft_mid(Z,Hp,tid);
.Lmy_pf_skipb:
	s_cmp_eq_u32 s89, 0
	s_cbranch_scc1 .Lmy_noH
	s_cmp_eq_u32 s89, 1
	s_cselect_b32 s98, s76, s78
	s_cselect_b32 s99, s77, s79
	v_lshrrev_b32_e32 v222, 6, v154
	v_bfe_u32 v223, v154, 4, 2
	v_lshlrev_b32_e32 v222, 8, v222
	v_lshl_add_u32 v222, v223, 11, v222
	v_and_b32_e32 v223, 15, v154
	v_lshl_add_u32 v222, v223, 4, v222
	v_lshlrev_b32_e32 v222, 2, v222
	global_load_dwordx4 v[170:173], v222, s[98:99] offset:0
	global_load_dwordx4 v[174:177], v222, s[98:99] offset:16
	global_load_dwordx4 v[178:181], v222, s[98:99] offset:32
	global_load_dwordx4 v[182:185], v222, s[98:99] offset:48
	v_add_u32_e32 v223, 0x8000, v222
	global_load_dwordx4 v[104:107], v223, s[98:99] offset:0
	global_load_dwordx4 v[108:111], v223, s[98:99] offset:16
	global_load_dwordx4 v[112:115], v223, s[98:99] offset:32
	global_load_dwordx4 v[116:119], v223, s[98:99] offset:48

; HD float2 cmul(float2 a, float2 b){ return make_float2(a.x*b.x - a.y*b.y, a.x*b.y + a.y*b.x); }
; template<bool INV, int LQ, bool BARRIER=true>
; HD void fft_pass(float2* Z, const float2* twA, const float2* twB, int tid){
;     ...
;   } else {
;     int j=tid&(q-1); int base0=((tid>>LQ)<<(LQ+2))+j;
;     float2 w1=make_float2(1.f,0.f), w2=w1, w3=w1;
;     if (LQ>0){ int k=j*tws; w1=cmul(twA[k>>6],twB[k&63]); w2=cmul(w1,w1); w3=cmul(w2,w1); }
;     _Pragma("unroll") for (int i=0;i<8;++i){ int base=base0+i*2048; bf4c<INV,(LQ==0)>(Z,base,base+q,base+2*q,base+3*q,w1,w2,w3); }
; __device__ __forceinline__ void fft_mid(float2* Z, const f16x2* Hp, int tid){
;   _Pragma("unroll 4") for (int i=0;i<8;++i){ int base=(tid<<2)+i*2048;
;     u32x4 hw=*(const u32x4*)(Hp+base);
;     unsigned hw0=hw[0], hw1=hw[1], hw2=hw[2], hw3=hw[3];
;     float2 a0=Z[base], a1=Z[base+1], a2=Z[base+2], a3=Z[base+3];
;     float2 s02=make_float2(a0.x+a2.x,a0.y+a2.y), d02=make_float2(a0.x-a2.x,a0.y-a2.y);
;     float2 s13=make_float2(a1.x+a3.x,a1.y+a3.y), d13=make_float2(a1.x-a3.x,a1.y-a3.y);
;     float2 y0=make_float2(s02.x+s13.x,s02.y+s13.y), y2=make_float2(s02.x-s13.x,s02.y-s13.y);
;     float2 y1=make_float2(d02.x+d13.y,d02.y-d13.x);
;     float2 y3=make_float2(d02.x-d13.y,d02.y+d13.x);
.Lmy_skip_lq2:
	v_add_u32_e32 v14, 0x4000, v169
	v_add_u32_e32 v15, 0x8000, v169
	v_add_u32_e32 v16, 0xc000, v169
	v_add_u32_e32 v17, 0x4000, v186
	v_add_u32_e32 v18, 0x8000, v186
	v_add_u32_e32 v19, 0xc000, v186
	s_mov_b64 s[12:13], -1
	s_and_b64 vcc, exec, s[68:69]
	s_cbranch_vccz .LBB0_1344
	s_cmp_lg_u32 s89, 1
	s_cselect_b64 s[50:51], -1, 0
	s_cmp_eq_u32 s89, 1
	s_cselect_b32 s69, s77, s79
	s_cselect_b32 s68, s76, s78
	v_mov_b32_e32 v68, 0x3f6c835e
	v_mov_b32_e32 v69, 0x3ec3ef15
	v_mov_b32_e32 v70, 0x3f3504f3
	v_mov_b32_e32 v71, 0x3f3504f3
	v_lshrrev_b32_e32 v225, 6, v154
	v_bfe_u32 v226, v154, 4, 2
	v_lshlrev_b32_e32 v225, 8, v225
	v_lshl_add_u32 v225, v226, 11, v225
	v_and_b32_e32 v226, 15, v154
	v_lshl_add_u32 v225, v226, 4, v225
	v_lshlrev_b32_e32 v222, 3, v225
	v_add_u32_e32 v223, 0x10000, v222
	v_lshlrev_b32_e32 v224, 2, v225
	v_bfe_u32 v225, v154, 1, 1
	v_cmp_eq_u32_e64 s[98:99], 1, v225
	v_lshlrev_b32_e32 v225, 4, v225
	s_nop 3
	v_add_u32_e32 v74, v222, v225
	v_sub_u32_e32 v75, v222, v225
	v_add_u32_e32 v80, v222, v225
	v_sub_u32_e32 v81, v222, v225
	ds_read_b128 v[0:3], v74 offset:0
	ds_read_b128 v[4:7], v75 offset:16
	ds_read_b128 v[8:11], v80 offset:32
	ds_read_b128 v[12:15], v81 offset:48
	ds_read_b128 v[16:19], v74 offset:64
	ds_read_b128 v[20:23], v75 offset:80
	ds_read_b128 v[24:27], v80 offset:96
	ds_read_b128 v[28:31], v81 offset:112
	s_waitcnt lgkmcnt(0)
	s_mov_b64 exec, s[98:99]
	v_swap_b32 v0, v4
	v_swap_b32 v1, v5
	v_swap_b32 v2, v6
	v_swap_b32 v3, v7
	v_swap_b32 v8, v12
	v_swap_b32 v9, v13
	v_swap_b32 v10, v14
	v_swap_b32 v11, v15
	v_swap_b32 v16, v20
	v_swap_b32 v17, v21
	v_swap_b32 v18, v22
	v_swap_b32 v19, v23
	v_swap_b32 v24, v28
	v_swap_b32 v25, v29
	v_swap_b32 v26, v30
	v_swap_b32 v27, v31
	s_mov_b64 exec, -1
	v_pk_add_f32 v[58:59], v[0:1], v[16:17]
	v_pk_add_f32 v[60:61], v[0:1], v[16:17] neg_lo:[0,1] neg_hi:[0,1]
	v_pk_add_f32 v[62:63], v[8:9], v[24:25]
	v_pk_add_f32 v[64:65], v[8:9], v[24:25] neg_lo:[0,1] neg_hi:[0,1]
	v_pk_add_f32 v[0:1], v[58:59], v[62:63]
	v_pk_add_f32 v[16:17], v[58:59], v[62:63] neg_lo:[0,1] neg_hi:[0,1]
	v_pk_add_f32 v[8:9], v[60:61], v[64:65] op_sel:[0,1] op_sel_hi:[1,0] neg_hi:[0,1]
	v_pk_add_f32 v[24:25], v[60:61], v[64:65] op_sel:[0,1] op_sel_hi:[1,0] neg_lo:[0,1]
	v_pk_add_f32 v[58:59], v[2:3], v[18:19]
	v_pk_add_f32 v[60:61], v[2:3], v[18:19] neg_lo:[0,1] neg_hi:[0,1]
	v_pk_add_f32 v[62:63], v[10:11], v[26:27]
	v_pk_add_f32 v[64:65], v[10:11], v[26:27] neg_lo:[0,1] neg_hi:[0,1]
	v_pk_add_f32 v[2:3], v[58:59], v[62:63]
	v_pk_add_f32 v[18:19], v[58:59], v[62:63] neg_lo:[0,1] neg_hi:[0,1]
	v_pk_add_f32 v[10:11], v[60:61], v[64:65] op_sel:[0,1] op_sel_hi:[1,0] neg_hi:[0,1]
	v_pk_add_f32 v[26:27], v[60:61], v[64:65] op_sel:[0,1] op_sel_hi:[1,0] neg_lo:[0,1]
	v_pk_mul_f32 v[66:67], v[10:11], v[68:69] op_sel:[1,1] op_sel_hi:[1,0] neg_lo:[0,1] neg_hi:[0,0]
	v_pk_fma_f32 v[10:11], v[10:11], v[68:69], v[66:67] op_sel:[0,0,0] op_sel_hi:[0,1,1] neg_lo:[0,0,1] neg_hi:[0,1,0]
	v_pk_mul_f32 v[66:67], v[18:19], v[70:71] op_sel:[1,1] op_sel_hi:[1,0] neg_lo:[0,1] neg_hi:[0,0]
	v_pk_fma_f32 v[18:19], v[18:19], v[70:71], v[66:67] op_sel:[0,0,0] op_sel_hi:[0,1,1] neg_lo:[0,0,1] neg_hi:[0,1,0]
	v_pk_mul_f32 v[66:67], v[26:27], v[68:69] op_sel:[1,0] op_sel_hi:[1,1] neg_lo:[0,1] neg_hi:[0,0]
	v_pk_fma_f32 v[26:27], v[26:27], v[68:69], v[66:67] op_sel:[0,1,0] op_sel_hi:[0,0,1] neg_lo:[0,0,1] neg_hi:[0,1,0]
	v_pk_add_f32 v[58:59], v[4:5], v[20:21]
	v_pk_add_f32 v[60:61], v[4:5], v[20:21] neg_lo:[0,1] neg_hi:[0,1]
	v_pk_add_f32 v[62:63], v[12:13], v[28:29]
	v_pk_add_f32 v[64:65], v[12:13], v[28:29] neg_lo:[0,1] neg_hi:[0,1]
	v_pk_add_f32 v[4:5], v[58:59], v[62:63]
	v_pk_add_f32 v[20:21], v[58:59], v[62:63] neg_lo:[0,1] neg_hi:[0,1]
	v_pk_add_f32 v[12:13], v[60:61], v[64:65] op_sel:[0,1] op_sel_hi:[1,0] neg_hi:[0,1]
	v_pk_add_f32 v[28:29], v[60:61], v[64:65] op_sel:[0,1] op_sel_hi:[1,0] neg_lo:[0,1]
	v_pk_mul_f32 v[66:67], v[12:13], v[70:71] op_sel:[1,1] op_sel_hi:[1,0] neg_lo:[0,1] neg_hi:[0,0]
	v_pk_fma_f32 v[12:13], v[12:13], v[70:71], v[66:67] op_sel:[0,0,0] op_sel_hi:[0,1,1] neg_lo:[0,0,1] neg_hi:[0,1,0]
	v_pk_add_f32 v[20:21], v[20:21], 0 op_sel:[1,0] op_sel_hi:[0,0] neg_hi:[1,0]
	v_pk_mul_f32 v[66:67], v[28:29], v[70:71] op_sel:[1,1] op_sel_hi:[1,0] neg_lo:[0,1] neg_hi:[0,1]
	v_pk_fma_f32 v[28:29], v[28:29], v[70:71], v[66:67] op_sel:[0,0,0] op_sel_hi:[0,1,1] neg_lo:[0,1,1] neg_hi:[0,1,0]
	v_pk_add_f32 v[58:59], v[6:7], v[22:23]
	v_pk_add_f32 v[60:61], v[6:7], v[22:23] neg_lo:[0,1] neg_hi:[0,1]
	v_pk_add_f32 v[62:63], v[14:15], v[30:31]
	v_pk_add_f32 v[64:65], v[14:15], v[30:31] neg_lo:[0,1] neg_hi:[0,1]
	v_pk_add_f32 v[6:7], v[58:59], v[62:63]
	v_pk_add_f32 v[22:23], v[58:59], v[62:63] neg_lo:[0,1] neg_hi:[0,1]
	v_pk_add_f32 v[14:15], v[60:61], v[64:65] op_sel:[0,1] op_sel_hi:[1,0] neg_hi:[0,1]
	v_pk_add_f32 v[30:31], v[60:61], v[64:65] op_sel:[0,1] op_sel_hi:[1,0] neg_lo:[0,1]
	v_pk_mul_f32 v[66:67], v[14:15], v[68:69] op_sel:[1,0] op_sel_hi:[1,1] neg_lo:[0,1] neg_hi:[0,0]
	v_pk_fma_f32 v[14:15], v[14:15], v[68:69], v[66:67] op_sel:[0,1,0] op_sel_hi:[0,0,1] neg_lo:[0,0,1] neg_hi:[0,1,0]
	v_pk_mul_f32 v[66:67], v[22:23], v[70:71] op_sel:[1,1] op_sel_hi:[1,0] neg_lo:[0,1] neg_hi:[0,1]
	v_pk_fma_f32 v[22:23], v[22:23], v[70:71], v[66:67] op_sel:[0,0,0] op_sel_hi:[0,1,1] neg_lo:[0,1,1] neg_hi:[0,1,0]
	v_pk_mul_f32 v[66:67], v[30:31], v[68:69] op_sel:[1,1] op_sel_hi:[1,0] neg_lo:[0,0] neg_hi:[0,1]
	v_pk_fma_f32 v[30:31], v[30:31], v[68:69], v[66:67] op_sel:[0,0,0] op_sel_hi:[0,1,1] neg_lo:[0,1,1] neg_hi:[0,0,0]
	v_pk_add_f32 v[58:59], v[0:1], v[4:5]
	v_pk_add_f32 v[60:61], v[0:1], v[4:5] neg_lo:[0,1] neg_hi:[0,1]
; HD float2 cmul(float2 a, float2 b){ return make_float2(a.x*b.x - a.y*b.y, a.x*b.y + a.y*b.x); }
; __device__ __forceinline__ void fft_mid(float2* Z, const f16x2* Hp, int tid){
;     ...
;     float2 a0=Z[base], a1=Z[base+1], a2=Z[base+2], a3=Z[base+3];
;     float2 s02=make_float2(a0.x+a2.x,a0.y+a2.y), d02=make_float2(a0.x-a2.x,a0.y-a2.y);
;     float2 s13=make_float2(a1.x+a3.x,a1.y+a3.y), d13=make_float2(a1.x-a3.x,a1.y-a3.y);
;     float2 y0=make_float2(s02.x+s13.x,s02.y+s13.y), y2=make_float2(s02.x-s13.x,s02.y-s13.y);
;     float2 y1=make_float2(d02.x+d13.y,d02.y-d13.x);
;     float2 y3=make_float2(d02.x-d13.y,d02.y+d13.x);
;     f16x2 h0=__builtin_bit_cast(f16x2,hw0), h1=__builtin_bit_cast(f16x2,hw1), h2=__builtin_bit_cast(f16x2,hw2), h3=__builtin_bit_cast(f16x2,hw3);
;     float2 b0=cmul(y0,make_float2((float)h0[0],(float)h0[1])), b1=cmul(y1,make_float2((float)h1[0],(float)h1[1]));
;     float2 b2=cmul(y2,make_float2((float)h2[0],(float)h2[1])), b3=cmul(y3,make_float2((float)h3[0],(float)h3[1]));
	v_pk_add_f32 v[62:63], v[2:3], v[6:7]
	v_pk_add_f32 v[64:65], v[2:3], v[6:7] neg_lo:[0,1] neg_hi:[0,1]
	v_pk_add_f32 v[0:1], v[58:59], v[62:63]
	v_pk_add_f32 v[4:5], v[58:59], v[62:63] neg_lo:[0,1] neg_hi:[0,1]
	v_pk_add_f32 v[2:3], v[60:61], v[64:65] op_sel:[0,1] op_sel_hi:[1,0] neg_hi:[0,1]
	v_pk_add_f32 v[6:7], v[60:61], v[64:65] op_sel:[0,1] op_sel_hi:[1,0] neg_lo:[0,1]
	v_pk_add_f32 v[58:59], v[8:9], v[12:13]
	v_pk_add_f32 v[60:61], v[8:9], v[12:13] neg_lo:[0,1] neg_hi:[0,1]
	v_pk_add_f32 v[62:63], v[10:11], v[14:15]
	v_pk_add_f32 v[64:65], v[10:11], v[14:15] neg_lo:[0,1] neg_hi:[0,1]
	v_pk_add_f32 v[8:9], v[58:59], v[62:63]
	v_pk_add_f32 v[12:13], v[58:59], v[62:63] neg_lo:[0,1] neg_hi:[0,1]
	v_pk_add_f32 v[10:11], v[60:61], v[64:65] op_sel:[0,1] op_sel_hi:[1,0] neg_hi:[0,1]
	v_pk_add_f32 v[14:15], v[60:61], v[64:65] op_sel:[0,1] op_sel_hi:[1,0] neg_lo:[0,1]
	v_pk_add_f32 v[58:59], v[16:17], v[20:21]
	v_pk_add_f32 v[60:61], v[16:17], v[20:21] neg_lo:[0,1] neg_hi:[0,1]
	v_pk_add_f32 v[62:63], v[18:19], v[22:23]
	v_pk_add_f32 v[64:65], v[18:19], v[22:23] neg_lo:[0,1] neg_hi:[0,1]
	v_pk_add_f32 v[16:17], v[58:59], v[62:63]
	v_pk_add_f32 v[20:21], v[58:59], v[62:63] neg_lo:[0,1] neg_hi:[0,1]
	v_pk_add_f32 v[18:19], v[60:61], v[64:65] op_sel:[0,1] op_sel_hi:[1,0] neg_hi:[0,1]
	v_pk_add_f32 v[22:23], v[60:61], v[64:65] op_sel:[0,1] op_sel_hi:[1,0] neg_lo:[0,1]
	v_pk_add_f32 v[58:59], v[24:25], v[28:29]
	v_pk_add_f32 v[60:61], v[24:25], v[28:29] neg_lo:[0,1] neg_hi:[0,1]
	v_pk_add_f32 v[62:63], v[26:27], v[30:31]
	v_pk_add_f32 v[64:65], v[26:27], v[30:31] neg_lo:[0,1] neg_hi:[0,1]
	v_pk_add_f32 v[24:25], v[58:59], v[62:63]
	v_pk_add_f32 v[28:29], v[58:59], v[62:63] neg_lo:[0,1] neg_hi:[0,1]
	v_pk_add_f32 v[26:27], v[60:61], v[64:65] op_sel:[0,1] op_sel_hi:[1,0] neg_hi:[0,1]
	v_pk_add_f32 v[30:31], v[60:61], v[64:65] op_sel:[0,1] op_sel_hi:[1,0] neg_lo:[0,1]
	s_waitcnt vmcnt(0)
	v_cvt_f32_f16_e32 v72, v170
	v_cvt_f32_f16_sdwa v73, v170 dst_sel:DWORD dst_unused:UNUSED_PAD src0_sel:WORD_1
	s_nop 0
	v_pk_mul_f32 v[66:67], v[0:1], v[72:73] op_sel:[1,1] op_sel_hi:[1,0]
	v_pk_fma_f32 v[0:1], v[0:1], v[72:73], v[66:67] op_sel:[0,0,0] op_sel_hi:[0,1,1] neg_lo:[0,0,1]
	v_cvt_f32_f16_e32 v72, v171
	v_cvt_f32_f16_sdwa v73, v171 dst_sel:DWORD dst_unused:UNUSED_PAD src0_sel:WORD_1
	s_nop 0
	v_pk_mul_f32 v[66:67], v[2:3], v[72:73] op_sel:[1,1] op_sel_hi:[1,0]
	v_pk_fma_f32 v[2:3], v[2:3], v[72:73], v[66:67] op_sel:[0,0,0] op_sel_hi:[0,1,1] neg_lo:[0,0,1]
	v_cvt_f32_f16_e32 v72, v172
	v_cvt_f32_f16_sdwa v73, v172 dst_sel:DWORD dst_unused:UNUSED_PAD src0_sel:WORD_1
	s_nop 0
	v_pk_mul_f32 v[66:67], v[4:5], v[72:73] op_sel:[1,1] op_sel_hi:[1,0]
	v_pk_fma_f32 v[4:5], v[4:5], v[72:73], v[66:67] op_sel:[0,0,0] op_sel_hi:[0,1,1] neg_lo:[0,0,1]
	v_cvt_f32_f16_e32 v72, v173
	v_cvt_f32_f16_sdwa v73, v173 dst_sel:DWORD dst_unused:UNUSED_PAD src0_sel:WORD_1
	s_nop 0
	v_pk_mul_f32 v[66:67], v[6:7], v[72:73] op_sel:[1,1] op_sel_hi:[1,0]
	v_pk_fma_f32 v[6:7], v[6:7], v[72:73], v[66:67] op_sel:[0,0,0] op_sel_hi:[0,1,1] neg_lo:[0,0,1]
	v_cvt_f32_f16_e32 v72, v174
	v_cvt_f32_f16_sdwa v73, v174 dst_sel:DWORD dst_unused:UNUSED_PAD src0_sel:WORD_1
	s_nop 0
	v_pk_mul_f32 v[66:67], v[8:9], v[72:73] op_sel:[1,1] op_sel_hi:[1,0]
	v_pk_fma_f32 v[8:9], v[8:9], v[72:73], v[66:67] op_sel:[0,0,0] op_sel_hi:[0,1,1] neg_lo:[0,0,1]
	v_cvt_f32_f16_e32 v72, v175
	v_cvt_f32_f16_sdwa v73, v175 dst_sel:DWORD dst_unused:UNUSED_PAD src0_sel:WORD_1
	s_nop 0
	v_pk_mul_f32 v[66:67], v[10:11], v[72:73] op_sel:[1,1] op_sel_hi:[1,0]
	v_pk_fma_f32 v[10:11], v[10:11], v[72:73], v[66:67] op_sel:[0,0,0] op_sel_hi:[0,1,1] neg_lo:[0,0,1]
	v_cvt_f32_f16_e32 v72, v176
	v_cvt_f32_f16_sdwa v73, v176 dst_sel:DWORD dst_unused:UNUSED_PAD src0_sel:WORD_1
	s_nop 0
	v_pk_mul_f32 v[66:67], v[12:13], v[72:73] op_sel:[1,1] op_sel_hi:[1,0]
	v_pk_fma_f32 v[12:13], v[12:13], v[72:73], v[66:67] op_sel:[0,0,0] op_sel_hi:[0,1,1] neg_lo:[0,0,1]
	v_cvt_f32_f16_e32 v72, v177
	v_cvt_f32_f16_sdwa v73, v177 dst_sel:DWORD dst_unused:UNUSED_PAD src0_sel:WORD_1
	s_nop 0
	v_pk_mul_f32 v[66:67], v[14:15], v[72:73] op_sel:[1,1] op_sel_hi:[1,0]
	v_pk_fma_f32 v[14:15], v[14:15], v[72:73], v[66:67] op_sel:[0,0,0] op_sel_hi:[0,1,1] neg_lo:[0,0,1]
	v_cvt_f32_f16_e32 v72, v178
	v_cvt_f32_f16_sdwa v73, v178 dst_sel:DWORD dst_unused:UNUSED_PAD src0_sel:WORD_1
	s_nop 0
	v_pk_mul_f32 v[66:67], v[16:17], v[72:73] op_sel:[1,1] op_sel_hi:[1,0]
	v_pk_fma_f32 v[16:17], v[16:17], v[72:73], v[66:67] op_sel:[0,0,0] op_sel_hi:[0,1,1] neg_lo:[0,0,1]
	v_cvt_f32_f16_e32 v72, v179
	v_cvt_f32_f16_sdwa v73, v179 dst_sel:DWORD dst_unused:UNUSED_PAD src0_sel:WORD_1
	s_nop 0
	v_pk_mul_f32 v[66:67], v[18:19], v[72:73] op_sel:[1,1] op_sel_hi:[1,0]
	v_pk_fma_f32 v[18:19], v[18:19], v[72:73], v[66:67] op_sel:[0,0,0] op_sel_hi:[0,1,1] neg_lo:[0,0,1]
	v_cvt_f32_f16_e32 v72, v180
	v_cvt_f32_f16_sdwa v73, v180 dst_sel:DWORD dst_unused:UNUSED_PAD src0_sel:WORD_1
	s_nop 0
	v_pk_mul_f32 v[66:67], v[20:21], v[72:73] op_sel:[1,1] op_sel_hi:[1,0]
	v_pk_fma_f32 v[20:21], v[20:21], v[72:73], v[66:67] op_sel:[0,0,0] op_sel_hi:[0,1,1] neg_lo:[0,0,1]
	v_cvt_f32_f16_e32 v72, v181
	v_cvt_f32_f16_sdwa v73, v181 dst_sel:DWORD dst_unused:UNUSED_PAD src0_sel:WORD_1
	s_nop 0
	v_pk_mul_f32 v[66:67], v[22:23], v[72:73] op_sel:[1,1] op_sel_hi:[1,0]
	v_pk_fma_f32 v[22:23], v[22:23], v[72:73], v[66:67] op_sel:[0,0,0] op_sel_hi:[0,1,1] neg_lo:[0,0,1]
	v_cvt_f32_f16_e32 v72, v182
	v_cvt_f32_f16_sdwa v73, v182 dst_sel:DWORD dst_unused:UNUSED_PAD src0_sel:WORD_1
	s_nop 0
	v_pk_mul_f32 v[66:67], v[24:25], v[72:73] op_sel:[1,1] op_sel_hi:[1,0]
	v_pk_fma_f32 v[24:25], v[24:25], v[72:73], v[66:67] op_sel:[0,0,0] op_sel_hi:[0,1,1] neg_lo:[0,0,1]
; HD float2 cmul(float2 a, float2 b){ return make_float2(a.x*b.x - a.y*b.y, a.x*b.y + a.y*b.x); }
; HD float2 cmulc(float2 a, float2 b){ return make_float2(a.x*b.x + a.y*b.y, a.y*b.x - a.x*b.y); }
; template<bool INV, bool NOTW>
; HD void bf4c(float2* Z, int i0, int i1, int i2, int i3, float2 w1, float2 w2, float2 w3){
;   float2 a0=Z[i0], a1=Z[i1], a2=Z[i2], a3=Z[i3];
;   if (INV && !NOTW){ a1=cmulc(a1,w1); a2=cmulc(a2,w2); a3=cmulc(a3,w3); }
;   float2 s02=make_float2(a0.x+a2.x,a0.y+a2.y), d02=make_float2(a0.x-a2.x,a0.y-a2.y);
;   float2 s13=make_float2(a1.x+a3.x,a1.y+a3.y), d13=make_float2(a1.x-a3.x,a1.y-a3.y);
;   float2 y0=make_float2(s02.x+s13.x,s02.y+s13.y), y2=make_float2(s02.x-s13.x,s02.y-s13.y);
;   float2 ym=make_float2(d02.x+d13.y,d02.y-d13.x);
;   float2 yp=make_float2(d02.x-d13.y,d02.y+d13.x);
;   float2 y1, y3;
;   if (INV){ y1=yp; y3=ym; } else if (NOTW){ y1=ym; y3=yp; } else { y1=cmul(ym,w1); y2=cmul(y2,w2); y3=cmul(yp,w3); }
;   Z[i0]=y0; Z[i1]=y1; Z[i2]=y2; Z[i3]=y3;
; __device__ __forceinline__ void fft_mid(float2* Z, const f16x2* Hp, int tid){
;     ...
;     float2 b0=cmul(y0,make_float2((float)h0[0],(float)h0[1])), b1=cmul(y1,make_float2((float)h1[0],(float)h1[1]));
;     float2 b2=cmul(y2,make_float2((float)h2[0],(float)h2[1])), b3=cmul(y3,make_float2((float)h3[0],(float)h3[1]));
;     float2 t02=make_float2(b0.x+b2.x,b0.y+b2.y), e02=make_float2(b0.x-b2.x,b0.y-b2.y);
;     float2 t13=make_float2(b1.x+b3.x,b1.y+b3.y), e13=make_float2(b1.x-b3.x,b1.y-b3.y);
;     Z[base]=make_float2(t02.x+t13.x,t02.y+t13.y); Z[base+2]=make_float2(t02.x-t13.x,t02.y-t13.y);
;     Z[base+1]=make_float2(e02.x-e13.y,e02.y+e13.x);
;     Z[base+3]=make_float2(e02.x+e13.y,e02.y-e13.x);
	v_cvt_f32_f16_e32 v72, v183
	v_cvt_f32_f16_sdwa v73, v183 dst_sel:DWORD dst_unused:UNUSED_PAD src0_sel:WORD_1
	s_nop 0
	v_pk_mul_f32 v[66:67], v[26:27], v[72:73] op_sel:[1,1] op_sel_hi:[1,0]
	v_pk_fma_f32 v[26:27], v[26:27], v[72:73], v[66:67] op_sel:[0,0,0] op_sel_hi:[0,1,1] neg_lo:[0,0,1]
	v_cvt_f32_f16_e32 v72, v184
	v_cvt_f32_f16_sdwa v73, v184 dst_sel:DWORD dst_unused:UNUSED_PAD src0_sel:WORD_1
	s_nop 0
	v_pk_mul_f32 v[66:67], v[28:29], v[72:73] op_sel:[1,1] op_sel_hi:[1,0]
	v_pk_fma_f32 v[28:29], v[28:29], v[72:73], v[66:67] op_sel:[0,0,0] op_sel_hi:[0,1,1] neg_lo:[0,0,1]
	v_cvt_f32_f16_e32 v72, v185
	v_cvt_f32_f16_sdwa v73, v185 dst_sel:DWORD dst_unused:UNUSED_PAD src0_sel:WORD_1
	s_nop 0
	v_pk_mul_f32 v[66:67], v[30:31], v[72:73] op_sel:[1,1] op_sel_hi:[1,0]
	v_pk_fma_f32 v[30:31], v[30:31], v[72:73], v[66:67] op_sel:[0,0,0] op_sel_hi:[0,1,1] neg_lo:[0,0,1]
	v_pk_add_f32 v[58:59], v[0:1], v[4:5]
	v_pk_add_f32 v[60:61], v[0:1], v[4:5] neg_lo:[0,1] neg_hi:[0,1]
	v_pk_add_f32 v[62:63], v[2:3], v[6:7]
	v_pk_add_f32 v[64:65], v[2:3], v[6:7] neg_lo:[0,1] neg_hi:[0,1]
	v_pk_add_f32 v[0:1], v[58:59], v[62:63]
	v_pk_add_f32 v[4:5], v[58:59], v[62:63] neg_lo:[0,1] neg_hi:[0,1]
	v_pk_add_f32 v[2:3], v[60:61], v[64:65] op_sel:[0,1] op_sel_hi:[1,0] neg_lo:[0,1]
	v_pk_add_f32 v[6:7], v[60:61], v[64:65] op_sel:[0,1] op_sel_hi:[1,0] neg_hi:[0,1]
	v_pk_add_f32 v[58:59], v[8:9], v[12:13]
	v_pk_add_f32 v[60:61], v[8:9], v[12:13] neg_lo:[0,1] neg_hi:[0,1]
	v_pk_add_f32 v[62:63], v[10:11], v[14:15]
	v_pk_add_f32 v[64:65], v[10:11], v[14:15] neg_lo:[0,1] neg_hi:[0,1]
	v_pk_add_f32 v[8:9], v[58:59], v[62:63]
	v_pk_add_f32 v[12:13], v[58:59], v[62:63] neg_lo:[0,1] neg_hi:[0,1]
	v_pk_add_f32 v[10:11], v[60:61], v[64:65] op_sel:[0,1] op_sel_hi:[1,0] neg_lo:[0,1]
	v_pk_add_f32 v[14:15], v[60:61], v[64:65] op_sel:[0,1] op_sel_hi:[1,0] neg_hi:[0,1]
	v_pk_add_f32 v[58:59], v[16:17], v[20:21]
	v_pk_add_f32 v[60:61], v[16:17], v[20:21] neg_lo:[0,1] neg_hi:[0,1]
	v_pk_add_f32 v[62:63], v[18:19], v[22:23]
	v_pk_add_f32 v[64:65], v[18:19], v[22:23] neg_lo:[0,1] neg_hi:[0,1]
	v_pk_add_f32 v[16:17], v[58:59], v[62:63]
	v_pk_add_f32 v[20:21], v[58:59], v[62:63] neg_lo:[0,1] neg_hi:[0,1]
	v_pk_add_f32 v[18:19], v[60:61], v[64:65] op_sel:[0,1] op_sel_hi:[1,0] neg_lo:[0,1]
	v_pk_add_f32 v[22:23], v[60:61], v[64:65] op_sel:[0,1] op_sel_hi:[1,0] neg_hi:[0,1]
	v_pk_add_f32 v[58:59], v[24:25], v[28:29]
	v_pk_add_f32 v[60:61], v[24:25], v[28:29] neg_lo:[0,1] neg_hi:[0,1]
	v_pk_add_f32 v[62:63], v[26:27], v[30:31]
	v_pk_add_f32 v[64:65], v[26:27], v[30:31] neg_lo:[0,1] neg_hi:[0,1]
	v_pk_add_f32 v[24:25], v[58:59], v[62:63]
	v_pk_add_f32 v[28:29], v[58:59], v[62:63] neg_lo:[0,1] neg_hi:[0,1]
	v_pk_add_f32 v[26:27], v[60:61], v[64:65] op_sel:[0,1] op_sel_hi:[1,0] neg_lo:[0,1]
	v_pk_add_f32 v[30:31], v[60:61], v[64:65] op_sel:[0,1] op_sel_hi:[1,0] neg_hi:[0,1]
	v_pk_add_f32 v[58:59], v[0:1], v[16:17]
	v_pk_add_f32 v[60:61], v[0:1], v[16:17] neg_lo:[0,1] neg_hi:[0,1]
	v_pk_add_f32 v[62:63], v[8:9], v[24:25]
	v_pk_add_f32 v[64:65], v[8:9], v[24:25] neg_lo:[0,1] neg_hi:[0,1]
	v_pk_add_f32 v[0:1], v[58:59], v[62:63]
	v_pk_add_f32 v[16:17], v[58:59], v[62:63] neg_lo:[0,1] neg_hi:[0,1]
	v_pk_add_f32 v[8:9], v[60:61], v[64:65] op_sel:[0,1] op_sel_hi:[1,0] neg_lo:[0,1]
	v_pk_add_f32 v[24:25], v[60:61], v[64:65] op_sel:[0,1] op_sel_hi:[1,0] neg_hi:[0,1]
	v_pk_mul_f32 v[66:67], v[10:11], v[68:69] op_sel:[1,1] op_sel_hi:[1,0] neg_lo:[0,0] neg_hi:[0,0]
	v_pk_fma_f32 v[10:11], v[10:11], v[68:69], v[66:67] op_sel:[0,0,0] op_sel_hi:[0,1,1] neg_lo:[0,0,1] neg_hi:[0,0,0]
	v_pk_mul_f32 v[66:67], v[18:19], v[70:71] op_sel:[1,1] op_sel_hi:[1,0] neg_lo:[0,0] neg_hi:[0,0]
	v_pk_fma_f32 v[18:19], v[18:19], v[70:71], v[66:67] op_sel:[0,0,0] op_sel_hi:[0,1,1] neg_lo:[0,0,1] neg_hi:[0,0,0]
	v_pk_mul_f32 v[66:67], v[26:27], v[68:69] op_sel:[1,0] op_sel_hi:[1,1] neg_lo:[0,0] neg_hi:[0,0]
	v_pk_fma_f32 v[26:27], v[26:27], v[68:69], v[66:67] op_sel:[0,1,0] op_sel_hi:[0,0,1] neg_lo:[0,0,1] neg_hi:[0,0,0]
	v_pk_add_f32 v[58:59], v[2:3], v[18:19]
	v_pk_add_f32 v[60:61], v[2:3], v[18:19] neg_lo:[0,1] neg_hi:[0,1]
	v_pk_add_f32 v[62:63], v[10:11], v[26:27]
	v_pk_add_f32 v[64:65], v[10:11], v[26:27] neg_lo:[0,1] neg_hi:[0,1]
	v_pk_add_f32 v[2:3], v[58:59], v[62:63]
	v_pk_add_f32 v[18:19], v[58:59], v[62:63] neg_lo:[0,1] neg_hi:[0,1]
	v_pk_add_f32 v[10:11], v[60:61], v[64:65] op_sel:[0,1] op_sel_hi:[1,0] neg_lo:[0,1]
	v_pk_add_f32 v[26:27], v[60:61], v[64:65] op_sel:[0,1] op_sel_hi:[1,0] neg_hi:[0,1]
	v_pk_mul_f32 v[66:67], v[12:13], v[70:71] op_sel:[1,1] op_sel_hi:[1,0] neg_lo:[0,0] neg_hi:[0,0]
	v_pk_fma_f32 v[12:13], v[12:13], v[70:71], v[66:67] op_sel:[0,0,0] op_sel_hi:[0,1,1] neg_lo:[0,0,1] neg_hi:[0,0,0]
	v_pk_add_f32 v[20:21], v[20:21], 0 op_sel:[1,0] op_sel_hi:[0,0] neg_lo:[1,0]
	v_pk_mul_f32 v[66:67], v[28:29], v[70:71] op_sel:[1,1] op_sel_hi:[1,0] neg_lo:[0,0] neg_hi:[0,1]
	v_pk_fma_f32 v[28:29], v[28:29], v[70:71], v[66:67] op_sel:[0,0,0] op_sel_hi:[0,1,1] neg_lo:[0,1,1] neg_hi:[0,0,0]
	v_pk_add_f32 v[58:59], v[4:5], v[20:21]
	v_pk_add_f32 v[60:61], v[4:5], v[20:21] neg_lo:[0,1] neg_hi:[0,1]
	v_pk_add_f32 v[62:63], v[12:13], v[28:29]
	v_pk_add_f32 v[64:65], v[12:13], v[28:29] neg_lo:[0,1] neg_hi:[0,1]
	v_pk_add_f32 v[4:5], v[58:59], v[62:63]
	v_pk_add_f32 v[20:21], v[58:59], v[62:63] neg_lo:[0,1] neg_hi:[0,1]
	v_pk_add_f32 v[12:13], v[60:61], v[64:65] op_sel:[0,1] op_sel_hi:[1,0] neg_lo:[0,1]
	v_pk_add_f32 v[28:29], v[60:61], v[64:65] op_sel:[0,1] op_sel_hi:[1,0] neg_hi:[0,1]
	v_pk_mul_f32 v[66:67], v[14:15], v[68:69] op_sel:[1,0] op_sel_hi:[1,1] neg_lo:[0,0] neg_hi:[0,0]
; HD float2 cmul(float2 a, float2 b){ return make_float2(a.x*b.x - a.y*b.y, a.x*b.y + a.y*b.x); }
; HD float2 cmulc(float2 a, float2 b){ return make_float2(a.x*b.x + a.y*b.y, a.y*b.x - a.x*b.y); }
; template<bool INV, bool NOTW>
; HD void bf4c(float2* Z, int i0, int i1, int i2, int i3, float2 w1, float2 w2, float2 w3){
;   float2 a0=Z[i0], a1=Z[i1], a2=Z[i2], a3=Z[i3];
;   if (INV && !NOTW){ a1=cmulc(a1,w1); a2=cmulc(a2,w2); a3=cmulc(a3,w3); }
;   float2 s02=make_float2(a0.x+a2.x,a0.y+a2.y), d02=make_float2(a0.x-a2.x,a0.y-a2.y);
;   float2 s13=make_float2(a1.x+a3.x,a1.y+a3.y), d13=make_float2(a1.x-a3.x,a1.y-a3.y);
;   float2 y0=make_float2(s02.x+s13.x,s02.y+s13.y), y2=make_float2(s02.x-s13.x,s02.y-s13.y);
;   float2 ym=make_float2(d02.x+d13.y,d02.y-d13.x);
;   float2 yp=make_float2(d02.x-d13.y,d02.y+d13.x);
;   float2 y1, y3;
;   if (INV){ y1=yp; y3=ym; } else if (NOTW){ y1=ym; y3=yp; } else { y1=cmul(ym,w1); y2=cmul(y2,w2); y3=cmul(yp,w3); }
;   Z[i0]=y0; Z[i1]=y1; Z[i2]=y2; Z[i3]=y3;
; __device__ __forceinline__ void fft_mid(float2* Z, const f16x2* Hp, int tid){
;   _Pragma("unroll 4") for (int i=0;i<8;++i){ int base=(tid<<2)+i*2048;
;     u32x4 hw=*(const u32x4*)(Hp+base);
;     unsigned hw0=hw[0], hw1=hw[1], hw2=hw[2], hw3=hw[3];
;     float2 a0=Z[base], a1=Z[base+1], a2=Z[base+2], a3=Z[base+3];
;     float2 s02=make_float2(a0.x+a2.x,a0.y+a2.y), d02=make_float2(a0.x-a2.x,a0.y-a2.y);
;     float2 s13=make_float2(a1.x+a3.x,a1.y+a3.y), d13=make_float2(a1.x-a3.x,a1.y-a3.y);
;     float2 y0=make_float2(s02.x+s13.x,s02.y+s13.y), y2=make_float2(s02.x-s13.x,s02.y-s13.y);
;     float2 y1=make_float2(d02.x+d13.y,d02.y-d13.x);
;     float2 y3=make_float2(d02.x-d13.y,d02.y+d13.x);
	v_pk_fma_f32 v[14:15], v[14:15], v[68:69], v[66:67] op_sel:[0,1,0] op_sel_hi:[0,0,1] neg_lo:[0,0,1] neg_hi:[0,0,0]
	v_pk_mul_f32 v[66:67], v[22:23], v[70:71] op_sel:[1,1] op_sel_hi:[1,0] neg_lo:[0,0] neg_hi:[0,1]
	v_pk_fma_f32 v[22:23], v[22:23], v[70:71], v[66:67] op_sel:[0,0,0] op_sel_hi:[0,1,1] neg_lo:[0,1,1] neg_hi:[0,0,0]
	v_pk_mul_f32 v[66:67], v[30:31], v[68:69] op_sel:[1,1] op_sel_hi:[1,0] neg_lo:[0,1] neg_hi:[0,1]
	v_pk_fma_f32 v[30:31], v[30:31], v[68:69], v[66:67] op_sel:[0,0,0] op_sel_hi:[0,1,1] neg_lo:[0,1,1] neg_hi:[0,1,0]
	v_pk_add_f32 v[58:59], v[6:7], v[22:23]
	v_pk_add_f32 v[60:61], v[6:7], v[22:23] neg_lo:[0,1] neg_hi:[0,1]
	v_pk_add_f32 v[62:63], v[14:15], v[30:31]
	v_pk_add_f32 v[64:65], v[14:15], v[30:31] neg_lo:[0,1] neg_hi:[0,1]
	v_pk_add_f32 v[6:7], v[58:59], v[62:63]
	v_pk_add_f32 v[22:23], v[58:59], v[62:63] neg_lo:[0,1] neg_hi:[0,1]
	v_pk_add_f32 v[14:15], v[60:61], v[64:65] op_sel:[0,1] op_sel_hi:[1,0] neg_lo:[0,1]
	v_pk_add_f32 v[30:31], v[60:61], v[64:65] op_sel:[0,1] op_sel_hi:[1,0] neg_hi:[0,1]
	s_mov_b64 exec, s[98:99]
	v_swap_b32 v0, v4
	v_swap_b32 v1, v5
	v_swap_b32 v2, v6
	v_swap_b32 v3, v7
	v_swap_b32 v8, v12
	v_swap_b32 v9, v13
	v_swap_b32 v10, v14
	v_swap_b32 v11, v15
	v_swap_b32 v16, v20
	v_swap_b32 v17, v21
	v_swap_b32 v18, v22
	v_swap_b32 v19, v23
	v_swap_b32 v24, v28
	v_swap_b32 v25, v29
	v_swap_b32 v26, v30
	v_swap_b32 v27, v31
	s_mov_b64 exec, -1
	ds_write_b128 v74, v[0:3] offset:0
	ds_write_b128 v75, v[4:7] offset:16
	ds_write_b128 v80, v[8:11] offset:32
	ds_write_b128 v81, v[12:15] offset:48
	ds_write_b128 v74, v[16:19] offset:64
	ds_write_b128 v75, v[20:23] offset:80
	ds_write_b128 v80, v[24:27] offset:96
	ds_write_b128 v81, v[28:31] offset:112
	v_add_u32_e32 v74, v223, v225
	v_sub_u32_e32 v75, v223, v225
	v_add_u32_e32 v80, v223, v225
	v_sub_u32_e32 v81, v223, v225
	ds_read_b128 v[0:3], v74 offset:0
	ds_read_b128 v[4:7], v75 offset:16
	ds_read_b128 v[8:11], v80 offset:32
	ds_read_b128 v[12:15], v81 offset:48
	ds_read_b128 v[16:19], v74 offset:64
	ds_read_b128 v[20:23], v75 offset:80
	ds_read_b128 v[24:27], v80 offset:96
	ds_read_b128 v[28:31], v81 offset:112
	s_waitcnt lgkmcnt(0)
	s_mov_b64 exec, s[98:99]
	v_swap_b32 v0, v4
	v_swap_b32 v1, v5
	v_swap_b32 v2, v6
	v_swap_b32 v3, v7
	v_swap_b32 v8, v12
	v_swap_b32 v9, v13
	v_swap_b32 v10, v14
	v_swap_b32 v11, v15
	v_swap_b32 v16, v20
	v_swap_b32 v17, v21
	v_swap_b32 v18, v22
	v_swap_b32 v19, v23
	v_swap_b32 v24, v28
	v_swap_b32 v25, v29
	v_swap_b32 v26, v30
	v_swap_b32 v27, v31
	s_mov_b64 exec, -1
	v_pk_add_f32 v[58:59], v[0:1], v[16:17]
	v_pk_add_f32 v[60:61], v[0:1], v[16:17] neg_lo:[0,1] neg_hi:[0,1]
	v_pk_add_f32 v[62:63], v[8:9], v[24:25]
	v_pk_add_f32 v[64:65], v[8:9], v[24:25] neg_lo:[0,1] neg_hi:[0,1]
	v_pk_add_f32 v[0:1], v[58:59], v[62:63]
	v_pk_add_f32 v[16:17], v[58:59], v[62:63] neg_lo:[0,1] neg_hi:[0,1]
	v_pk_add_f32 v[8:9], v[60:61], v[64:65] op_sel:[0,1] op_sel_hi:[1,0] neg_hi:[0,1]
	v_pk_add_f32 v[24:25], v[60:61], v[64:65] op_sel:[0,1] op_sel_hi:[1,0] neg_lo:[0,1]
	v_pk_add_f32 v[58:59], v[2:3], v[18:19]
	v_pk_add_f32 v[60:61], v[2:3], v[18:19] neg_lo:[0,1] neg_hi:[0,1]
	v_pk_add_f32 v[62:63], v[10:11], v[26:27]
	v_pk_add_f32 v[64:65], v[10:11], v[26:27] neg_lo:[0,1] neg_hi:[0,1]
	v_pk_add_f32 v[2:3], v[58:59], v[62:63]
	v_pk_add_f32 v[18:19], v[58:59], v[62:63] neg_lo:[0,1] neg_hi:[0,1]
	v_pk_add_f32 v[10:11], v[60:61], v[64:65] op_sel:[0,1] op_sel_hi:[1,0] neg_hi:[0,1]
	v_pk_add_f32 v[26:27], v[60:61], v[64:65] op_sel:[0,1] op_sel_hi:[1,0] neg_lo:[0,1]
	v_pk_mul_f32 v[66:67], v[10:11], v[68:69] op_sel:[1,1] op_sel_hi:[1,0] neg_lo:[0,1] neg_hi:[0,0]
	v_pk_fma_f32 v[10:11], v[10:11], v[68:69], v[66:67] op_sel:[0,0,0] op_sel_hi:[0,1,1] neg_lo:[0,0,1] neg_hi:[0,1,0]
	v_pk_mul_f32 v[66:67], v[18:19], v[70:71] op_sel:[1,1] op_sel_hi:[1,0] neg_lo:[0,1] neg_hi:[0,0]
	v_pk_fma_f32 v[18:19], v[18:19], v[70:71], v[66:67] op_sel:[0,0,0] op_sel_hi:[0,1,1] neg_lo:[0,0,1] neg_hi:[0,1,0]
	v_pk_mul_f32 v[66:67], v[26:27], v[68:69] op_sel:[1,0] op_sel_hi:[1,1] neg_lo:[0,1] neg_hi:[0,0]
	v_pk_fma_f32 v[26:27], v[26:27], v[68:69], v[66:67] op_sel:[0,1,0] op_sel_hi:[0,0,1] neg_lo:[0,0,1] neg_hi:[0,1,0]
	v_pk_add_f32 v[58:59], v[4:5], v[20:21]
	v_pk_add_f32 v[60:61], v[4:5], v[20:21] neg_lo:[0,1] neg_hi:[0,1]
	v_pk_add_f32 v[62:63], v[12:13], v[28:29]
	v_pk_add_f32 v[64:65], v[12:13], v[28:29] neg_lo:[0,1] neg_hi:[0,1]
	v_pk_add_f32 v[4:5], v[58:59], v[62:63]
	v_pk_add_f32 v[20:21], v[58:59], v[62:63] neg_lo:[0,1] neg_hi:[0,1]
	v_pk_add_f32 v[12:13], v[60:61], v[64:65] op_sel:[0,1] op_sel_hi:[1,0] neg_hi:[0,1]
	v_pk_add_f32 v[28:29], v[60:61], v[64:65] op_sel:[0,1] op_sel_hi:[1,0] neg_lo:[0,1]
	v_pk_mul_f32 v[66:67], v[12:13], v[70:71] op_sel:[1,1] op_sel_hi:[1,0] neg_lo:[0,1] neg_hi:[0,0]
	v_pk_fma_f32 v[12:13], v[12:13], v[70:71], v[66:67] op_sel:[0,0,0] op_sel_hi:[0,1,1] neg_lo:[0,0,1] neg_hi:[0,1,0]
	v_pk_add_f32 v[20:21], v[20:21], 0 op_sel:[1,0] op_sel_hi:[0,0] neg_hi:[1,0]
	v_pk_mul_f32 v[66:67], v[28:29], v[70:71] op_sel:[1,1] op_sel_hi:[1,0] neg_lo:[0,1] neg_hi:[0,1]
	v_pk_fma_f32 v[28:29], v[28:29], v[70:71], v[66:67] op_sel:[0,0,0] op_sel_hi:[0,1,1] neg_lo:[0,1,1] neg_hi:[0,1,0]
	v_pk_add_f32 v[58:59], v[6:7], v[22:23]
	v_pk_add_f32 v[60:61], v[6:7], v[22:23] neg_lo:[0,1] neg_hi:[0,1]
	v_pk_add_f32 v[62:63], v[14:15], v[30:31]
	v_pk_add_f32 v[64:65], v[14:15], v[30:31] neg_lo:[0,1] neg_hi:[0,1]
	v_pk_add_f32 v[6:7], v[58:59], v[62:63]
	v_pk_add_f32 v[22:23], v[58:59], v[62:63] neg_lo:[0,1] neg_hi:[0,1]
	v_pk_add_f32 v[14:15], v[60:61], v[64:65] op_sel:[0,1] op_sel_hi:[1,0] neg_hi:[0,1]
	v_pk_add_f32 v[30:31], v[60:61], v[64:65] op_sel:[0,1] op_sel_hi:[1,0] neg_lo:[0,1]
; HD float2 cmul(float2 a, float2 b){ return make_float2(a.x*b.x - a.y*b.y, a.x*b.y + a.y*b.x); }
; __device__ __forceinline__ void fft_mid(float2* Z, const f16x2* Hp, int tid){
;     ...
;     float2 a0=Z[base], a1=Z[base+1], a2=Z[base+2], a3=Z[base+3];
;     float2 s02=make_float2(a0.x+a2.x,a0.y+a2.y), d02=make_float2(a0.x-a2.x,a0.y-a2.y);
;     float2 s13=make_float2(a1.x+a3.x,a1.y+a3.y), d13=make_float2(a1.x-a3.x,a1.y-a3.y);
;     float2 y0=make_float2(s02.x+s13.x,s02.y+s13.y), y2=make_float2(s02.x-s13.x,s02.y-s13.y);
;     float2 y1=make_float2(d02.x+d13.y,d02.y-d13.x);
;     float2 y3=make_float2(d02.x-d13.y,d02.y+d13.x);
;     f16x2 h0=__builtin_bit_cast(f16x2,hw0), h1=__builtin_bit_cast(f16x2,hw1), h2=__builtin_bit_cast(f16x2,hw2), h3=__builtin_bit_cast(f16x2,hw3);
;     float2 b0=cmul(y0,make_float2((float)h0[0],(float)h0[1])), b1=cmul(y1,make_float2((float)h1[0],(float)h1[1]));
;     float2 b2=cmul(y2,make_float2((float)h2[0],(float)h2[1])), b3=cmul(y3,make_float2((float)h3[0],(float)h3[1]));
	v_pk_mul_f32 v[66:67], v[14:15], v[68:69] op_sel:[1,0] op_sel_hi:[1,1] neg_lo:[0,1] neg_hi:[0,0]
	v_pk_fma_f32 v[14:15], v[14:15], v[68:69], v[66:67] op_sel:[0,1,0] op_sel_hi:[0,0,1] neg_lo:[0,0,1] neg_hi:[0,1,0]
	v_pk_mul_f32 v[66:67], v[22:23], v[70:71] op_sel:[1,1] op_sel_hi:[1,0] neg_lo:[0,1] neg_hi:[0,1]
	v_pk_fma_f32 v[22:23], v[22:23], v[70:71], v[66:67] op_sel:[0,0,0] op_sel_hi:[0,1,1] neg_lo:[0,1,1] neg_hi:[0,1,0]
	v_pk_mul_f32 v[66:67], v[30:31], v[68:69] op_sel:[1,1] op_sel_hi:[1,0] neg_lo:[0,0] neg_hi:[0,1]
	v_pk_fma_f32 v[30:31], v[30:31], v[68:69], v[66:67] op_sel:[0,0,0] op_sel_hi:[0,1,1] neg_lo:[0,1,1] neg_hi:[0,0,0]
	v_pk_add_f32 v[58:59], v[0:1], v[4:5]
	v_pk_add_f32 v[60:61], v[0:1], v[4:5] neg_lo:[0,1] neg_hi:[0,1]
	v_pk_add_f32 v[62:63], v[2:3], v[6:7]
	v_pk_add_f32 v[64:65], v[2:3], v[6:7] neg_lo:[0,1] neg_hi:[0,1]
	v_pk_add_f32 v[0:1], v[58:59], v[62:63]
	v_pk_add_f32 v[4:5], v[58:59], v[62:63] neg_lo:[0,1] neg_hi:[0,1]
	v_pk_add_f32 v[2:3], v[60:61], v[64:65] op_sel:[0,1] op_sel_hi:[1,0] neg_hi:[0,1]
	v_pk_add_f32 v[6:7], v[60:61], v[64:65] op_sel:[0,1] op_sel_hi:[1,0] neg_lo:[0,1]
	v_pk_add_f32 v[58:59], v[8:9], v[12:13]
	v_pk_add_f32 v[60:61], v[8:9], v[12:13] neg_lo:[0,1] neg_hi:[0,1]
	v_pk_add_f32 v[62:63], v[10:11], v[14:15]
	v_pk_add_f32 v[64:65], v[10:11], v[14:15] neg_lo:[0,1] neg_hi:[0,1]
	v_pk_add_f32 v[8:9], v[58:59], v[62:63]
	v_pk_add_f32 v[12:13], v[58:59], v[62:63] neg_lo:[0,1] neg_hi:[0,1]
	v_pk_add_f32 v[10:11], v[60:61], v[64:65] op_sel:[0,1] op_sel_hi:[1,0] neg_hi:[0,1]
	v_pk_add_f32 v[14:15], v[60:61], v[64:65] op_sel:[0,1] op_sel_hi:[1,0] neg_lo:[0,1]
	v_pk_add_f32 v[58:59], v[16:17], v[20:21]
	v_pk_add_f32 v[60:61], v[16:17], v[20:21] neg_lo:[0,1] neg_hi:[0,1]
	v_pk_add_f32 v[62:63], v[18:19], v[22:23]
	v_pk_add_f32 v[64:65], v[18:19], v[22:23] neg_lo:[0,1] neg_hi:[0,1]
	v_pk_add_f32 v[16:17], v[58:59], v[62:63]
	v_pk_add_f32 v[20:21], v[58:59], v[62:63] neg_lo:[0,1] neg_hi:[0,1]
	v_pk_add_f32 v[18:19], v[60:61], v[64:65] op_sel:[0,1] op_sel_hi:[1,0] neg_hi:[0,1]
	v_pk_add_f32 v[22:23], v[60:61], v[64:65] op_sel:[0,1] op_sel_hi:[1,0] neg_lo:[0,1]
	v_pk_add_f32 v[58:59], v[24:25], v[28:29]
	v_pk_add_f32 v[60:61], v[24:25], v[28:29] neg_lo:[0,1] neg_hi:[0,1]
	v_pk_add_f32 v[62:63], v[26:27], v[30:31]
	v_pk_add_f32 v[64:65], v[26:27], v[30:31] neg_lo:[0,1] neg_hi:[0,1]
	v_pk_add_f32 v[24:25], v[58:59], v[62:63]
	v_pk_add_f32 v[28:29], v[58:59], v[62:63] neg_lo:[0,1] neg_hi:[0,1]
	v_pk_add_f32 v[26:27], v[60:61], v[64:65] op_sel:[0,1] op_sel_hi:[1,0] neg_hi:[0,1]
	v_pk_add_f32 v[30:31], v[60:61], v[64:65] op_sel:[0,1] op_sel_hi:[1,0] neg_lo:[0,1]
	s_waitcnt vmcnt(0)
	v_cvt_f32_f16_e32 v72, v104
	v_cvt_f32_f16_sdwa v73, v104 dst_sel:DWORD dst_unused:UNUSED_PAD src0_sel:WORD_1
	s_nop 0
	v_pk_mul_f32 v[66:67], v[0:1], v[72:73] op_sel:[1,1] op_sel_hi:[1,0]
	v_pk_fma_f32 v[0:1], v[0:1], v[72:73], v[66:67] op_sel:[0,0,0] op_sel_hi:[0,1,1] neg_lo:[0,0,1]
	v_cvt_f32_f16_e32 v72, v105
	v_cvt_f32_f16_sdwa v73, v105 dst_sel:DWORD dst_unused:UNUSED_PAD src0_sel:WORD_1
	s_nop 0
	v_pk_mul_f32 v[66:67], v[2:3], v[72:73] op_sel:[1,1] op_sel_hi:[1,0]
	v_pk_fma_f32 v[2:3], v[2:3], v[72:73], v[66:67] op_sel:[0,0,0] op_sel_hi:[0,1,1] neg_lo:[0,0,1]
	v_cvt_f32_f16_e32 v72, v106
	v_cvt_f32_f16_sdwa v73, v106 dst_sel:DWORD dst_unused:UNUSED_PAD src0_sel:WORD_1
	s_nop 0
	v_pk_mul_f32 v[66:67], v[4:5], v[72:73] op_sel:[1,1] op_sel_hi:[1,0]
	v_pk_fma_f32 v[4:5], v[4:5], v[72:73], v[66:67] op_sel:[0,0,0] op_sel_hi:[0,1,1] neg_lo:[0,0,1]
	v_cvt_f32_f16_e32 v72, v107
	v_cvt_f32_f16_sdwa v73, v107 dst_sel:DWORD dst_unused:UNUSED_PAD src0_sel:WORD_1
	s_nop 0
	v_pk_mul_f32 v[66:67], v[6:7], v[72:73] op_sel:[1,1] op_sel_hi:[1,0]
	v_pk_fma_f32 v[6:7], v[6:7], v[72:73], v[66:67] op_sel:[0,0,0] op_sel_hi:[0,1,1] neg_lo:[0,0,1]
	v_cvt_f32_f16_e32 v72, v108
	v_cvt_f32_f16_sdwa v73, v108 dst_sel:DWORD dst_unused:UNUSED_PAD src0_sel:WORD_1
	s_nop 0
	v_pk_mul_f32 v[66:67], v[8:9], v[72:73] op_sel:[1,1] op_sel_hi:[1,0]
	v_pk_fma_f32 v[8:9], v[8:9], v[72:73], v[66:67] op_sel:[0,0,0] op_sel_hi:[0,1,1] neg_lo:[0,0,1]
	v_cvt_f32_f16_e32 v72, v109
	v_cvt_f32_f16_sdwa v73, v109 dst_sel:DWORD dst_unused:UNUSED_PAD src0_sel:WORD_1
	s_nop 0
	v_pk_mul_f32 v[66:67], v[10:11], v[72:73] op_sel:[1,1] op_sel_hi:[1,0]
	v_pk_fma_f32 v[10:11], v[10:11], v[72:73], v[66:67] op_sel:[0,0,0] op_sel_hi:[0,1,1] neg_lo:[0,0,1]
	v_cvt_f32_f16_e32 v72, v110
	v_cvt_f32_f16_sdwa v73, v110 dst_sel:DWORD dst_unused:UNUSED_PAD src0_sel:WORD_1
	s_nop 0
	v_pk_mul_f32 v[66:67], v[12:13], v[72:73] op_sel:[1,1] op_sel_hi:[1,0]
	v_pk_fma_f32 v[12:13], v[12:13], v[72:73], v[66:67] op_sel:[0,0,0] op_sel_hi:[0,1,1] neg_lo:[0,0,1]
	v_cvt_f32_f16_e32 v72, v111
	v_cvt_f32_f16_sdwa v73, v111 dst_sel:DWORD dst_unused:UNUSED_PAD src0_sel:WORD_1
	s_nop 0
	v_pk_mul_f32 v[66:67], v[14:15], v[72:73] op_sel:[1,1] op_sel_hi:[1,0]
	v_pk_fma_f32 v[14:15], v[14:15], v[72:73], v[66:67] op_sel:[0,0,0] op_sel_hi:[0,1,1] neg_lo:[0,0,1]
	v_cvt_f32_f16_e32 v72, v112
	v_cvt_f32_f16_sdwa v73, v112 dst_sel:DWORD dst_unused:UNUSED_PAD src0_sel:WORD_1
	s_nop 0
	v_pk_mul_f32 v[66:67], v[16:17], v[72:73] op_sel:[1,1] op_sel_hi:[1,0]
	v_pk_fma_f32 v[16:17], v[16:17], v[72:73], v[66:67] op_sel:[0,0,0] op_sel_hi:[0,1,1] neg_lo:[0,0,1]
	v_cvt_f32_f16_e32 v72, v113
	v_cvt_f32_f16_sdwa v73, v113 dst_sel:DWORD dst_unused:UNUSED_PAD src0_sel:WORD_1
	s_nop 0
	v_pk_mul_f32 v[66:67], v[18:19], v[72:73] op_sel:[1,1] op_sel_hi:[1,0]
	v_pk_fma_f32 v[18:19], v[18:19], v[72:73], v[66:67] op_sel:[0,0,0] op_sel_hi:[0,1,1] neg_lo:[0,0,1]
	v_cvt_f32_f16_e32 v72, v114
	v_cvt_f32_f16_sdwa v73, v114 dst_sel:DWORD dst_unused:UNUSED_PAD src0_sel:WORD_1
; HD float2 cmul(float2 a, float2 b){ return make_float2(a.x*b.x - a.y*b.y, a.x*b.y + a.y*b.x); }
; __device__ __forceinline__ void fft_mid(float2* Z, const f16x2* Hp, int tid){
;     ...
;     float2 b0=cmul(y0,make_float2((float)h0[0],(float)h0[1])), b1=cmul(y1,make_float2((float)h1[0],(float)h1[1]));
;     float2 b2=cmul(y2,make_float2((float)h2[0],(float)h2[1])), b3=cmul(y3,make_float2((float)h3[0],(float)h3[1]));
;     float2 t02=make_float2(b0.x+b2.x,b0.y+b2.y), e02=make_float2(b0.x-b2.x,b0.y-b2.y);
;     float2 t13=make_float2(b1.x+b3.x,b1.y+b3.y), e13=make_float2(b1.x-b3.x,b1.y-b3.y);
;     Z[base]=make_float2(t02.x+t13.x,t02.y+t13.y); Z[base+2]=make_float2(t02.x-t13.x,t02.y-t13.y);
;     Z[base+1]=make_float2(e02.x-e13.y,e02.y+e13.x);
;     Z[base+3]=make_float2(e02.x+e13.y,e02.y-e13.x);
	s_nop 0
	v_pk_mul_f32 v[66:67], v[20:21], v[72:73] op_sel:[1,1] op_sel_hi:[1,0]
	v_pk_fma_f32 v[20:21], v[20:21], v[72:73], v[66:67] op_sel:[0,0,0] op_sel_hi:[0,1,1] neg_lo:[0,0,1]
	v_cvt_f32_f16_e32 v72, v115
	v_cvt_f32_f16_sdwa v73, v115 dst_sel:DWORD dst_unused:UNUSED_PAD src0_sel:WORD_1
	s_nop 0
	v_pk_mul_f32 v[66:67], v[22:23], v[72:73] op_sel:[1,1] op_sel_hi:[1,0]
	v_pk_fma_f32 v[22:23], v[22:23], v[72:73], v[66:67] op_sel:[0,0,0] op_sel_hi:[0,1,1] neg_lo:[0,0,1]
	v_cvt_f32_f16_e32 v72, v116
	v_cvt_f32_f16_sdwa v73, v116 dst_sel:DWORD dst_unused:UNUSED_PAD src0_sel:WORD_1
	s_nop 0
	v_pk_mul_f32 v[66:67], v[24:25], v[72:73] op_sel:[1,1] op_sel_hi:[1,0]
	v_pk_fma_f32 v[24:25], v[24:25], v[72:73], v[66:67] op_sel:[0,0,0] op_sel_hi:[0,1,1] neg_lo:[0,0,1]
	v_cvt_f32_f16_e32 v72, v117
	v_cvt_f32_f16_sdwa v73, v117 dst_sel:DWORD dst_unused:UNUSED_PAD src0_sel:WORD_1
	s_nop 0
	v_pk_mul_f32 v[66:67], v[26:27], v[72:73] op_sel:[1,1] op_sel_hi:[1,0]
	v_pk_fma_f32 v[26:27], v[26:27], v[72:73], v[66:67] op_sel:[0,0,0] op_sel_hi:[0,1,1] neg_lo:[0,0,1]
	v_cvt_f32_f16_e32 v72, v118
	v_cvt_f32_f16_sdwa v73, v118 dst_sel:DWORD dst_unused:UNUSED_PAD src0_sel:WORD_1
	s_nop 0
	v_pk_mul_f32 v[66:67], v[28:29], v[72:73] op_sel:[1,1] op_sel_hi:[1,0]
	v_pk_fma_f32 v[28:29], v[28:29], v[72:73], v[66:67] op_sel:[0,0,0] op_sel_hi:[0,1,1] neg_lo:[0,0,1]
	v_cvt_f32_f16_e32 v72, v119
	v_cvt_f32_f16_sdwa v73, v119 dst_sel:DWORD dst_unused:UNUSED_PAD src0_sel:WORD_1
	s_nop 0
	v_pk_mul_f32 v[66:67], v[30:31], v[72:73] op_sel:[1,1] op_sel_hi:[1,0]
	v_pk_fma_f32 v[30:31], v[30:31], v[72:73], v[66:67] op_sel:[0,0,0] op_sel_hi:[0,1,1] neg_lo:[0,0,1]
	v_pk_add_f32 v[58:59], v[0:1], v[4:5]
	v_pk_add_f32 v[60:61], v[0:1], v[4:5] neg_lo:[0,1] neg_hi:[0,1]
	v_pk_add_f32 v[62:63], v[2:3], v[6:7]
	v_pk_add_f32 v[64:65], v[2:3], v[6:7] neg_lo:[0,1] neg_hi:[0,1]
	v_pk_add_f32 v[0:1], v[58:59], v[62:63]
	v_pk_add_f32 v[4:5], v[58:59], v[62:63] neg_lo:[0,1] neg_hi:[0,1]
	v_pk_add_f32 v[2:3], v[60:61], v[64:65] op_sel:[0,1] op_sel_hi:[1,0] neg_lo:[0,1]
	v_pk_add_f32 v[6:7], v[60:61], v[64:65] op_sel:[0,1] op_sel_hi:[1,0] neg_hi:[0,1]
	v_pk_add_f32 v[58:59], v[8:9], v[12:13]
	v_pk_add_f32 v[60:61], v[8:9], v[12:13] neg_lo:[0,1] neg_hi:[0,1]
	v_pk_add_f32 v[62:63], v[10:11], v[14:15]
	v_pk_add_f32 v[64:65], v[10:11], v[14:15] neg_lo:[0,1] neg_hi:[0,1]
	v_pk_add_f32 v[8:9], v[58:59], v[62:63]
	v_pk_add_f32 v[12:13], v[58:59], v[62:63] neg_lo:[0,1] neg_hi:[0,1]
	v_pk_add_f32 v[10:11], v[60:61], v[64:65] op_sel:[0,1] op_sel_hi:[1,0] neg_lo:[0,1]
	v_pk_add_f32 v[14:15], v[60:61], v[64:65] op_sel:[0,1] op_sel_hi:[1,0] neg_hi:[0,1]
	v_pk_add_f32 v[58:59], v[16:17], v[20:21]
	v_pk_add_f32 v[60:61], v[16:17], v[20:21] neg_lo:[0,1] neg_hi:[0,1]
	v_pk_add_f32 v[62:63], v[18:19], v[22:23]
	v_pk_add_f32 v[64:65], v[18:19], v[22:23] neg_lo:[0,1] neg_hi:[0,1]
	v_pk_add_f32 v[16:17], v[58:59], v[62:63]
	v_pk_add_f32 v[20:21], v[58:59], v[62:63] neg_lo:[0,1] neg_hi:[0,1]
	v_pk_add_f32 v[18:19], v[60:61], v[64:65] op_sel:[0,1] op_sel_hi:[1,0] neg_lo:[0,1]
	v_pk_add_f32 v[22:23], v[60:61], v[64:65] op_sel:[0,1] op_sel_hi:[1,0] neg_hi:[0,1]
	v_pk_add_f32 v[58:59], v[24:25], v[28:29]
	v_pk_add_f32 v[60:61], v[24:25], v[28:29] neg_lo:[0,1] neg_hi:[0,1]
	v_pk_add_f32 v[62:63], v[26:27], v[30:31]
	v_pk_add_f32 v[64:65], v[26:27], v[30:31] neg_lo:[0,1] neg_hi:[0,1]
	v_pk_add_f32 v[24:25], v[58:59], v[62:63]
	v_pk_add_f32 v[28:29], v[58:59], v[62:63] neg_lo:[0,1] neg_hi:[0,1]
	v_pk_add_f32 v[26:27], v[60:61], v[64:65] op_sel:[0,1] op_sel_hi:[1,0] neg_lo:[0,1]
	v_pk_add_f32 v[30:31], v[60:61], v[64:65] op_sel:[0,1] op_sel_hi:[1,0] neg_hi:[0,1]
	v_pk_add_f32 v[58:59], v[0:1], v[16:17]
	v_pk_add_f32 v[60:61], v[0:1], v[16:17] neg_lo:[0,1] neg_hi:[0,1]
	v_pk_add_f32 v[62:63], v[8:9], v[24:25]
	v_pk_add_f32 v[64:65], v[8:9], v[24:25] neg_lo:[0,1] neg_hi:[0,1]
	v_pk_add_f32 v[0:1], v[58:59], v[62:63]
	v_pk_add_f32 v[16:17], v[58:59], v[62:63] neg_lo:[0,1] neg_hi:[0,1]
	v_pk_add_f32 v[8:9], v[60:61], v[64:65] op_sel:[0,1] op_sel_hi:[1,0] neg_lo:[0,1]
	v_pk_add_f32 v[24:25], v[60:61], v[64:65] op_sel:[0,1] op_sel_hi:[1,0] neg_hi:[0,1]
	v_pk_mul_f32 v[66:67], v[10:11], v[68:69] op_sel:[1,1] op_sel_hi:[1,0] neg_lo:[0,0] neg_hi:[0,0]
; __device__ __forceinline__ void fft_mid(float2* Z, const f16x2* Hp, int tid){
;     ...
;     Z[base]=make_float2(t02.x+t13.x,t02.y+t13.y); Z[base+2]=make_float2(t02.x-t13.x,t02.y-t13.y);
;     Z[base+1]=make_float2(e02.x-e13.y,e02.y+e13.x);
;     Z[base+3]=make_float2(e02.x+e13.y,e02.y-e13.x);
; __device__ __forceinline__ void phase_hyena(KP kp_, int hf){ asm volatile("" : "+s"(kp_)); const Params p=load_params(kp_);
;     ...
;         const f16x2* Hp = st==1 ? H0p : H1p;
;         fft_mid(Z,Hp,tid);
;         fft_inv_tail(Z,twA,twB,tid);
;         if (st==1){ int tq=tid; asm volatile("" : "+v"(tq));
;           _Pragma("unroll 4") for (int i=0;i<8;++i){ int tb=tq+512*i; float2 xr[2]; inv12_half(Z,twA,twB,tb,xr[0],xr[1]);
	v_pk_fma_f32 v[10:11], v[10:11], v[68:69], v[66:67] op_sel:[0,0,0] op_sel_hi:[0,1,1] neg_lo:[0,0,1] neg_hi:[0,0,0]
	v_pk_mul_f32 v[66:67], v[18:19], v[70:71] op_sel:[1,1] op_sel_hi:[1,0] neg_lo:[0,0] neg_hi:[0,0]
	v_pk_fma_f32 v[18:19], v[18:19], v[70:71], v[66:67] op_sel:[0,0,0] op_sel_hi:[0,1,1] neg_lo:[0,0,1] neg_hi:[0,0,0]
	v_pk_mul_f32 v[66:67], v[26:27], v[68:69] op_sel:[1,0] op_sel_hi:[1,1] neg_lo:[0,0] neg_hi:[0,0]
	v_pk_fma_f32 v[26:27], v[26:27], v[68:69], v[66:67] op_sel:[0,1,0] op_sel_hi:[0,0,1] neg_lo:[0,0,1] neg_hi:[0,0,0]
	v_pk_add_f32 v[58:59], v[2:3], v[18:19]
	v_pk_add_f32 v[60:61], v[2:3], v[18:19] neg_lo:[0,1] neg_hi:[0,1]
	v_pk_add_f32 v[62:63], v[10:11], v[26:27]
	v_pk_add_f32 v[64:65], v[10:11], v[26:27] neg_lo:[0,1] neg_hi:[0,1]
	v_pk_add_f32 v[2:3], v[58:59], v[62:63]
	v_pk_add_f32 v[18:19], v[58:59], v[62:63] neg_lo:[0,1] neg_hi:[0,1]
	v_pk_add_f32 v[10:11], v[60:61], v[64:65] op_sel:[0,1] op_sel_hi:[1,0] neg_lo:[0,1]
	v_pk_add_f32 v[26:27], v[60:61], v[64:65] op_sel:[0,1] op_sel_hi:[1,0] neg_hi:[0,1]
	v_pk_mul_f32 v[66:67], v[12:13], v[70:71] op_sel:[1,1] op_sel_hi:[1,0] neg_lo:[0,0] neg_hi:[0,0]
	v_pk_fma_f32 v[12:13], v[12:13], v[70:71], v[66:67] op_sel:[0,0,0] op_sel_hi:[0,1,1] neg_lo:[0,0,1] neg_hi:[0,0,0]
	v_pk_add_f32 v[20:21], v[20:21], 0 op_sel:[1,0] op_sel_hi:[0,0] neg_lo:[1,0]
	v_pk_mul_f32 v[66:67], v[28:29], v[70:71] op_sel:[1,1] op_sel_hi:[1,0] neg_lo:[0,0] neg_hi:[0,1]
	v_pk_fma_f32 v[28:29], v[28:29], v[70:71], v[66:67] op_sel:[0,0,0] op_sel_hi:[0,1,1] neg_lo:[0,1,1] neg_hi:[0,0,0]
	v_pk_add_f32 v[58:59], v[4:5], v[20:21]
	v_pk_add_f32 v[60:61], v[4:5], v[20:21] neg_lo:[0,1] neg_hi:[0,1]
	v_pk_add_f32 v[62:63], v[12:13], v[28:29]
	v_pk_add_f32 v[64:65], v[12:13], v[28:29] neg_lo:[0,1] neg_hi:[0,1]
	v_pk_add_f32 v[4:5], v[58:59], v[62:63]
	v_pk_add_f32 v[20:21], v[58:59], v[62:63] neg_lo:[0,1] neg_hi:[0,1]
	v_pk_add_f32 v[12:13], v[60:61], v[64:65] op_sel:[0,1] op_sel_hi:[1,0] neg_lo:[0,1]
	v_pk_add_f32 v[28:29], v[60:61], v[64:65] op_sel:[0,1] op_sel_hi:[1,0] neg_hi:[0,1]
	v_pk_mul_f32 v[66:67], v[14:15], v[68:69] op_sel:[1,0] op_sel_hi:[1,1] neg_lo:[0,0] neg_hi:[0,0]
	v_pk_fma_f32 v[14:15], v[14:15], v[68:69], v[66:67] op_sel:[0,1,0] op_sel_hi:[0,0,1] neg_lo:[0,0,1] neg_hi:[0,0,0]
	v_pk_mul_f32 v[66:67], v[22:23], v[70:71] op_sel:[1,1] op_sel_hi:[1,0] neg_lo:[0,0] neg_hi:[0,1]
	v_pk_fma_f32 v[22:23], v[22:23], v[70:71], v[66:67] op_sel:[0,0,0] op_sel_hi:[0,1,1] neg_lo:[0,1,1] neg_hi:[0,0,0]
	v_pk_mul_f32 v[66:67], v[30:31], v[68:69] op_sel:[1,1] op_sel_hi:[1,0] neg_lo:[0,1] neg_hi:[0,1]
	v_pk_fma_f32 v[30:31], v[30:31], v[68:69], v[66:67] op_sel:[0,0,0] op_sel_hi:[0,1,1] neg_lo:[0,1,1] neg_hi:[0,1,0]
	v_pk_add_f32 v[58:59], v[6:7], v[22:23]
	v_pk_add_f32 v[60:61], v[6:7], v[22:23] neg_lo:[0,1] neg_hi:[0,1]
	v_pk_add_f32 v[62:63], v[14:15], v[30:31]
	v_pk_add_f32 v[64:65], v[14:15], v[30:31] neg_lo:[0,1] neg_hi:[0,1]
	v_pk_add_f32 v[6:7], v[58:59], v[62:63]
	v_pk_add_f32 v[22:23], v[58:59], v[62:63] neg_lo:[0,1] neg_hi:[0,1]
	v_pk_add_f32 v[14:15], v[60:61], v[64:65] op_sel:[0,1] op_sel_hi:[1,0] neg_lo:[0,1]
	v_pk_add_f32 v[30:31], v[60:61], v[64:65] op_sel:[0,1] op_sel_hi:[1,0] neg_hi:[0,1]
	s_mov_b64 exec, s[98:99]
	v_swap_b32 v0, v4
	v_swap_b32 v1, v5
	v_swap_b32 v2, v6
	v_swap_b32 v3, v7
	v_swap_b32 v8, v12
	v_swap_b32 v9, v13
	v_swap_b32 v10, v14
	v_swap_b32 v11, v15
	v_swap_b32 v16, v20
	v_swap_b32 v17, v21
	v_swap_b32 v18, v22
	v_swap_b32 v19, v23
	v_swap_b32 v24, v28
	v_swap_b32 v25, v29
	v_swap_b32 v26, v30
	v_swap_b32 v27, v31
	s_mov_b64 exec, -1
	ds_write_b128 v74, v[0:3] offset:0
	ds_write_b128 v75, v[4:7] offset:16
	ds_write_b128 v80, v[8:11] offset:32
	ds_write_b128 v81, v[12:15] offset:48
	ds_write_b128 v74, v[16:19] offset:64
	ds_write_b128 v75, v[20:23] offset:80
	ds_write_b128 v80, v[24:27] offset:96
	ds_write_b128 v81, v[28:31] offset:112
	s_waitcnt lgkmcnt(0)
	s_mov_b64 s[18:19], 0x8000
	v_lshlrev_b32_e32 v232, 4, v154
	s_lshl_b32 s100, s90, 15
	v_add_u32_e32 v233, 0x2000, v232
	v_add_u32_e32 v234, 0x4000, v232
	v_add_u32_e32 v235, 0x6000, v232
	s_add_u32 s98, s70, 0x42bd000
	s_addc_u32 s99, s71, 0
	s_add_u32 s98, s98, s100
	s_addc_u32 s99, s99, 0
	s_cmp_eq_u32 s89, 1
	s_cbranch_scc1 .Lmy_pf_st1
	s_add_u32 s98, s98, 0x2000000
	s_addc_u32 s99, s99, 0
